# K-fragment LDS reads software-pipelined across the diff loop back-edge (issued in previous iteration stage 3), specialised fast-path PV copy
# baseline (speedup 1.0000x reference)
; #define LAS __attribute__((address_space(3)))
; #define MFMA32(a, b, c) __builtin_amdgcn_mfma_f32_32x32x16_bf16((a), (b), (c), 0, 0, 0)
; template <bool FOX> ...
;     ...
;         if (act) {
;             bf16x8 kf[8];
; #pragma unroll
;             for (int s = 0; s < 4; ++s) { kf[2 * s] = *(LAS const bf16x8*)(kb + koff[s]); kf[2 * s + 1] = *(LAS const bf16x8*)(kb + koff[s] + 8192); }
;             if (have_next2) ATT_DMA(tn2, (buf + 2) & 3);
;             if (FOX) {
;                 LAS const float* ck = (LAS const float*)(lds + ATT_CK + buf * 512) + 64 * stream;
;                 ckfirst = ck[0] * LOG2E;
;                 ck += 8 * hi;
;                 const float cqm = cq2 - mref;
; #pragma unroll
;                 for (int rr = 0; rr < 2; ++rr) {
;                     const f32x4 a0 = *(LAS const f32x4*)(ck + 16 * rr), a1 = *(LAS const f32x4*)(ck + 16 * rr + 4), b0 = *(LAS const f32x4*)(ck + 32 + 16 * rr), b1 = *(LAS const f32x4*)(ck + 32 + 16 * rr + 4);
; #pragma unroll
;                     for (int e = 0; e < 4; ++e) { s0[8 * rr + e] = cqm - LOG2E * a0[e]; s0[8 * rr + 4 + e] = cqm - LOG2E * a1[e]; s1[8 * rr + e] = cqm - LOG2E * b0[e]; s1[8 * rr + 4 + e] = cqm - LOG2E * b1[e]; }
;                 }
;                 ATT_SB();
;                 s0 = MFMA32(kf[0], qf[0], s0); s1 = MFMA32(kf[1], qf[0], s1);
;             } else {
;                 ATT_SB();
;                 s0 = MFMA32(kf[0], qf[0], negm); s1 = MFMA32(kf[1], qf[0], negm);
;             }
; #pragma unroll
;             for (int s = 1; s < 4; ++s) { s0 = MFMA32(kf[2 * s], qf[s], s0); s1 = MFMA32(kf[2 * s + 1], qf[s], s1); }
;     ...
;         ATT_MM(va, 0); ATT_VRD(va, 1); ATT_EXPCH(s0, 0, pf[0]); ATT_SB();
;         ATT_MM(va, 1); ATT_VRD(va, 2); ATT_EXPCH(s0, 8, pf[1]); ATT_SB();
;         ATT_MM(va, 2); ATT_VRD(va, 3); ATT_EXPCH(s1, 0, pf[2]); ATT_SB();
;         ATT_MM(va, 3); ATT_EXPCH(s1, 8, pf[3]); ATT_SB();
;         lsum += ps2.x + ps2.y;
;         if (resc) {
; #pragma unroll
;             for (int cb = 0; cb < NCB; ++cb)
; #pragma unroll
;                 for (int r = 0; r < 16; ++r) o[cb][r] *= alpha_o;
;         }
;         pbuf = buf;
;         if (FOX && act) wmore = __any(ub - mref > ckfirst) != 0;
;         bool cont = have_next;
;         if (FOX) { if (lane == 0) flags[buf * 8 + wid] = wmore ? 1 : 0; }
;         ATT_WAIT_BAR(have_next2);
.Ldiff_noprio:
	s_lshl_b32 s7, s22, 1
	s_mov_b32 s6, 1
	s_mov_b32 s23, 0
	s_sub_i32 s18, 0, s7
	s_movk_i32 s19, 0xff80
	s_movk_i32 s16, 0x100
	v_mov_b32_e32 v97, v96
	v_mov_b32_e32 v98, v96
	v_mov_b32_e32 v99, v96
	v_mov_b32_e32 v100, v96
	v_mov_b32_e32 v101, v96
	v_mov_b32_e32 v102, v96
	v_mov_b32_e32 v103, v96
	v_mov_b32_e32 v104, v96
	v_mov_b32_e32 v105, v96
	v_mov_b32_e32 v106, v96
	v_mov_b32_e32 v107, v96
	v_mov_b32_e32 v108, v96
	v_mov_b32_e32 v109, v96
	v_mov_b32_e32 v110, v96
	v_mov_b32_e32 v111, v96
.LBB0_562:
	s_add_i32 s14, s19, 0x82
	s_cmp_lt_u32 s14, s0
	s_cbranch_scc0 .Ldiff_slow
	s_cmp_le_u32 s14, s1
	s_cbranch_scc0 .Ldiff_slow
	s_cmp_eq_u64 s[8:9], 0
	s_cbranch_scc0 .Ldiff_slow
	s_mov_b32 s22, s6
	s_lshl_b32 s25, s22, 15
	s_lshl_b32 s29, s23, 15
	v_add_u32_e32 v17, s25, v238
	ds_read_b128 v[112:115], v17
	ds_read_b128 v[172:175], v17 offset:8192
	v_add_u32_e32 v17, s25, v239
	ds_read_b128 v[176:179], v17
	ds_read_b128 v[164:167], v17 offset:8192
	v_add_u32_e32 v17, s25, v240
	ds_read_b128 v[168:171], v17
	ds_read_b128 v[22:25], v17 offset:8192
	v_add_u32_e32 v17, s25, v241
	ds_read_b128 v[26:29], v17
	ds_read_b128 v[18:21], v17 offset:8192
.Ldiff_fast_warm:
	s_xor_b32 s15, s25, 0x10000
	s_lshl_b64 s[6:7], s[16:17], 10
	s_add_i32 s15, s24, s15
	s_add_i32 s25, s15, 0x400
	s_add_i32 s28, s15, 0x4000
	s_mov_b32 m0, s15
	v_lshl_add_u64 v[30:31], v[200:201], 0, s[6:7]
	s_waitcnt lgkmcnt(0)
	v_mfma_f32_32x32x16_bf16 v[128:143], v[112:115], v[2:5], v[96:111]
	global_load_lds_dwordx4 v[30:31], off
	s_mov_b32 m0, s25
	v_lshl_add_u64 v[30:31], v[198:199], 0, s[6:7]
	v_mfma_f32_32x32x16_bf16 v[128:143], v[176:179], v[6:9], v[128:143]
	v_mfma_f32_32x32x16_bf16 v[112:127], v[172:175], v[2:5], v[96:111]
	global_load_lds_dwordx4 v[30:31], off
	s_mov_b32 m0, s28
	v_lshl_add_u64 v[30:31], v[196:197], 0, s[6:7]
	v_add_u32_e32 v172, s29, v209
	v_add_u32_e32 v173, s29, v237
	v_mfma_f32_32x32x16_bf16 v[112:127], v[164:167], v[6:9], v[112:127]
	v_mfma_f32_32x32x16_bf16 v[128:143], v[168:171], v[10:13], v[128:143]
	global_load_lds_dwordx4 v[30:31], off
	v_lshl_add_u64 v[30:31], v[202:203], 0, s[6:7]
	s_add_i32 s6, s15, 0x4400
	s_mov_b32 m0, s6
	ds_read_b64_tr_b16 v[164:165], v172 offset:16384
	ds_read_b64_tr_b16 v[166:167], v173 offset:16384
	v_add_u32_e32 v168, s29, v205
	v_add_u32_e32 v169, s29, v206
	v_add_u32_e32 v170, s29, v207
	v_add_u32_e32 v171, s29, v208
	v_mfma_f32_32x32x16_bf16 v[112:127], v[22:25], v[10:13], v[112:127]
	v_mfma_f32_32x32x16_bf16 v[128:143], v[26:29], v[144:147], v[128:143]
	global_load_lds_dwordx4 v[30:31], off
	ds_read_b64_tr_b16 v[22:23], v168 offset:16384
	ds_read_b64_tr_b16 v[24:25], v169 offset:16384
	ds_read_b64_tr_b16 v[26:27], v170 offset:16384
	ds_read_b64_tr_b16 v[28:29], v171 offset:16384
	v_mfma_f32_32x32x16_bf16 v[112:127], v[18:21], v[144:147], v[112:127]
	v_add_u32_e32 v17, s29, v193
	v_add_u32_e32 v31, s29, v204
	ds_read_b64_tr_b16 v[18:19], v17 offset:16384
	ds_read_b64_tr_b16 v[20:21], v31 offset:16384
	s_waitcnt lgkmcnt(0)
	v_mfma_f32_32x32x16_bf16 v[80:95], v[18:21], v[148:151], v[80:95]
	v_exp_f32_e32 v128, v128
	v_exp_f32_e32 v129, v129
	v_exp_f32_e32 v130, v130
	ds_read_b64_tr_b16 v[18:19], v17 offset:20480
	ds_read_b64_tr_b16 v[20:21], v31 offset:20480
	v_mfma_f32_32x32x16_bf16 v[64:79], v[22:25], v[148:151], v[64:79]
	v_exp_f32_e32 v131, v131
	v_exp_f32_e32 v132, v132
	v_add_f32_e32 v254, v128, v130
	v_add_f32_e32 v255, v129, v131
	ds_read_b64_tr_b16 v[22:23], v168 offset:20480
	ds_read_b64_tr_b16 v[24:25], v169 offset:20480
	v_mfma_f32_32x32x16_bf16 v[48:63], v[26:29], v[148:151], v[48:63]
	v_exp_f32_e32 v133, v133
	v_exp_f32_e32 v134, v134
	v_add_f32_e32 v254, v254, v132
	v_add_f32_e32 v255, v255, v133
	ds_read_b64_tr_b16 v[26:27], v170 offset:20480
	ds_read_b64_tr_b16 v[28:29], v171 offset:20480
	v_mfma_f32_32x32x16_bf16 v[32:47], v[164:167], v[148:151], v[32:47]
	v_exp_f32_e32 v135, v135
	v_add_f32_e32 v254, v254, v134
	ds_read_b64_tr_b16 v[164:165], v172 offset:20480
	ds_read_b64_tr_b16 v[166:167], v173 offset:20480
	v_add_f32_e32 v255, v255, v135
	v_cvt_pk_bf16_f32 v148, v128, v129
	v_cvt_pk_bf16_f32 v149, v130, v131
	v_cvt_pk_bf16_f32 v150, v132, v133
	v_cvt_pk_bf16_f32 v151, v134, v135
	s_waitcnt lgkmcnt(0)
	v_mfma_f32_32x32x16_bf16 v[80:95], v[18:21], v[152:155], v[80:95]
	v_exp_f32_e32 v136, v136
	v_exp_f32_e32 v137, v137
	v_exp_f32_e32 v138, v138
	ds_read_b64_tr_b16 v[18:19], v17 offset:24576
	ds_read_b64_tr_b16 v[20:21], v31 offset:24576
	v_mfma_f32_32x32x16_bf16 v[64:79], v[22:25], v[152:155], v[64:79]
	v_exp_f32_e32 v139, v139
	v_exp_f32_e32 v140, v140
	v_add_f32_e32 v254, v254, v136
	v_add_f32_e32 v255, v255, v137
	ds_read_b64_tr_b16 v[22:23], v168 offset:24576
	ds_read_b64_tr_b16 v[24:25], v169 offset:24576
	v_mfma_f32_32x32x16_bf16 v[48:63], v[26:29], v[152:155], v[48:63]
	v_exp_f32_e32 v141, v141
	v_exp_f32_e32 v142, v142
	v_add_f32_e32 v254, v254, v138
	v_add_f32_e32 v255, v255, v139
	ds_read_b64_tr_b16 v[26:27], v170 offset:24576
	ds_read_b64_tr_b16 v[28:29], v171 offset:24576
	v_mfma_f32_32x32x16_bf16 v[32:47], v[164:167], v[152:155], v[32:47]
	v_exp_f32_e32 v143, v143
	v_add_f32_e32 v254, v254, v140
	v_add_f32_e32 v255, v255, v141
	ds_read_b64_tr_b16 v[164:165], v172 offset:24576
	ds_read_b64_tr_b16 v[166:167], v173 offset:24576
	v_add_f32_e32 v254, v254, v142
	v_add_f32_e32 v255, v255, v143
	v_cvt_pk_bf16_f32 v152, v136, v137
	v_cvt_pk_bf16_f32 v153, v138, v139
	v_cvt_pk_bf16_f32 v154, v140, v141
	v_cvt_pk_bf16_f32 v155, v142, v143
	s_waitcnt lgkmcnt(0)
	v_mfma_f32_32x32x16_bf16 v[80:95], v[18:21], v[160:163], v[80:95]
	v_exp_f32_e32 v112, v112
	v_exp_f32_e32 v113, v113
	v_exp_f32_e32 v114, v114
	ds_read_b64_tr_b16 v[18:19], v17 offset:28672
	ds_read_b64_tr_b16 v[20:21], v31 offset:28672
	v_mfma_f32_32x32x16_bf16 v[64:79], v[22:25], v[160:163], v[64:79]
	v_exp_f32_e32 v115, v115
	v_exp_f32_e32 v116, v116
	v_add_f32_e32 v254, v254, v112
	v_add_f32_e32 v255, v255, v113
	ds_read_b64_tr_b16 v[22:23], v168 offset:28672
	ds_read_b64_tr_b16 v[24:25], v169 offset:28672
	v_mfma_f32_32x32x16_bf16 v[48:63], v[26:29], v[160:163], v[48:63]
	v_exp_f32_e32 v117, v117
	v_exp_f32_e32 v118, v118
	v_add_f32_e32 v254, v254, v114
	v_add_f32_e32 v255, v255, v115
	ds_read_b64_tr_b16 v[26:27], v170 offset:28672
	ds_read_b64_tr_b16 v[28:29], v171 offset:28672
	v_mfma_f32_32x32x16_bf16 v[32:47], v[164:167], v[160:163], v[32:47]
	v_exp_f32_e32 v119, v119
	v_add_f32_e32 v254, v254, v116
	v_add_f32_e32 v255, v255, v117
	ds_read_b64_tr_b16 v[164:165], v172 offset:28672
	ds_read_b64_tr_b16 v[166:167], v173 offset:28672
	v_add_f32_e32 v254, v254, v118
	v_add_f32_e32 v255, v255, v119
	v_cvt_pk_bf16_f32 v160, v112, v113
	v_cvt_pk_bf16_f32 v161, v114, v115
	v_cvt_pk_bf16_f32 v162, v116, v117
	v_cvt_pk_bf16_f32 v163, v118, v119
	s_waitcnt lgkmcnt(0)
	s_waitcnt vmcnt(4)
	s_barrier
; #define LAS __attribute__((address_space(3)))
; __device__ __forceinline__ int rfl(int v) { return __builtin_amdgcn_readfirstlane(v); }
; #define ATT_WAIT_BAR(pending) do { if (pending) { if (FOX) asm volatile("s_waitcnt vmcnt(5) lgkmcnt(0)\n\ts_barrier" ::: "memory"); else asm volatile("s_waitcnt vmcnt(4) lgkmcnt(0)\n\ts_barrier" ::: "memory"); } \
;         else asm volatile("s_waitcnt vmcnt(0) lgkmcnt(0)\n\ts_barrier" ::: "memory"); } while (0)
; #define ATT_SB() __builtin_amdgcn_sched_barrier(0)
; #define ATT_MM(arr, ks) do { _Pragma("unroll") for (int cb = 0; cb < NCB; ++cb) { const bf16x8 vf = {arr[cb][0][0], arr[cb][0][1], arr[cb][0][2], arr[cb][0][3], arr[cb][1][0], arr[cb][1][1], arr[cb][1][2], arr[cb][1][3]}; o[cb] = MFMA32(vf, pf[ks], o[cb]); } } while (0)
; template <bool FOX> ...
;     ...
;             for (int s = 0; s < 4; ++s) { kf[2 * s] = *(LAS const bf16x8*)(kb + koff[s]); kf[2 * s + 1] = *(LAS const bf16x8*)(kb + koff[s] + 8192); }
;     ...
;         ATT_MM(va, 3); ATT_EXPCH(s1, 8, pf[3]); ATT_SB();
;         lsum += ps2.x + ps2.y;
;         if (resc) {
; #pragma unroll
;             for (int cb = 0; cb < NCB; ++cb)
; #pragma unroll
;                 for (int r = 0; r < 16; ++r) o[cb][r] *= alpha_o;
;         }
;         pbuf = buf;
;         if (FOX && act) wmore = __any(ub - mref > ckfirst) != 0;
;         bool cont = have_next;
;         if (FOX) { if (lane == 0) flags[buf * 8 + wid] = wmore ? 1 : 0; }
;         ATT_WAIT_BAR(have_next2);
;         if (FOX && cont) { int any_ = 0;
; #pragma unroll
;             for (int w8 = 0; w8 < 8; ++w8) any_ |= flags[buf * 8 + w8];
;             cont = rfl(any_) != 0; }
;         if (!cont) break;
;         t = tn; buf = nbuf;
	s_add_i32 s6, s22, 1
	s_and_b32 s6, s6, 3
	s_lshl_b32 s25, s6, 15
	v_add_u32_e32 v17, s25, v238
	v_add_u32_e32 v31, s25, v239
	v_add_u32_e32 v30, s25, v241
	ds_read_b128 v[112:115], v17
	ds_read_b128 v[172:175], v17 offset:8192
	ds_read_b128 v[176:179], v31
	v_add_u32_e32 v17, s25, v240
	v_mfma_f32_32x32x16_bf16 v[80:95], v[18:21], v[156:159], v[80:95]
	v_exp_f32_e32 v120, v120
	v_exp_f32_e32 v121, v121
	v_exp_f32_e32 v122, v122
	ds_read_b128 v[168:171], v17
	ds_read_b128 v[18:21], v30 offset:8192
	v_mfma_f32_32x32x16_bf16 v[64:79], v[22:25], v[156:159], v[64:79]
	v_exp_f32_e32 v123, v123
	v_exp_f32_e32 v124, v124
	v_add_f32_e32 v254, v254, v120
	v_add_f32_e32 v255, v255, v121
	ds_read_b128 v[22:25], v17 offset:8192
	v_mfma_f32_32x32x16_bf16 v[48:63], v[26:29], v[156:159], v[48:63]
	v_exp_f32_e32 v125, v125
	v_exp_f32_e32 v126, v126
	v_add_f32_e32 v254, v254, v122
	v_add_f32_e32 v255, v255, v123
	ds_read_b128 v[26:29], v30
	v_mfma_f32_32x32x16_bf16 v[32:47], v[164:167], v[156:159], v[32:47]
	v_exp_f32_e32 v127, v127
	v_add_f32_e32 v254, v254, v124
	v_add_f32_e32 v255, v255, v125
	ds_read_b128 v[164:167], v31 offset:8192
	v_add_f32_e32 v254, v254, v126
	v_add_f32_e32 v255, v255, v127
	v_cvt_pk_bf16_f32 v156, v120, v121
	v_cvt_pk_bf16_f32 v157, v122, v123
	v_cvt_pk_bf16_f32 v158, v124, v125
	v_cvt_pk_bf16_f32 v159, v126, v127
	v_add_f32_e32 v17, v254, v255
	s_add_i32 s19, s19, 1
	s_add_i32 s16, s16, 64
	s_cmp_lg_u32 s18, s19
	v_add_f32_e32 v244, v244, v17
	s_cbranch_scc0 .Ldiff_fast_exit
	s_mov_b32 s23, s22
	s_add_i32 s14, s19, 0x82
	s_cmp_lt_u32 s14, s0
	s_cbranch_scc0 .Ldiff_fast_fallback
	s_cmp_le_u32 s14, s1
	s_cbranch_scc0 .Ldiff_fast_fallback
	s_mov_b32 s22, s6
	s_lshl_b32 s29, s23, 15
	s_branch .Ldiff_fast_warm
.Ldiff_fast_fallback:
	s_waitcnt lgkmcnt(0)
	s_branch .LBB0_562
